# M3 epilogue (head-norm + output gate): per step the two loads are issued before the previous step's store and waited with counted vmcnt(2)/(1), so the store no longer sits on the per-step critical pat
# baseline (speedup 1.0000x reference)
.LBB0_1033:
	s_or_b64 exec, exec, s[20:21]
	s_waitcnt lgkmcnt(0)
	s_barrier
	s_and_saveexec_b64 s[20:21], s[16:17]
	s_cbranch_execz .LBB0_977
	ds_read_b128 v[10:13], v203
	ds_read_b128 v[14:17], v203 offset:32
	v_mov_b32_e32 v205, v51
	v_mov_b32_e32 v211, v51
	v_mov_b32_e32 v213, v27
	s_waitcnt lgkmcnt(1)
	v_mov_b32_e32 v30, v11
	v_mov_b32_e32 v31, v12
	v_mov_b32_e32 v11, v13
	v_pk_add_f32 v[76:77], v[72:73], v[30:31]
	v_pk_add_f32 v[74:75], v[74:75], v[10:11]
	v_pk_mul_f32 v[10:11], v[76:77], v[76:77]
	s_lshl_b32 s60, s62, 8
	v_pk_fma_f32 v[10:11], v[74:75], v[74:75], v[10:11]
	s_mov_b32 s61, s43
	v_pk_add_f32 v[30:31], v[10:11], v[10:11] op_sel:[0,1] op_sel_hi:[1,0]
	s_waitcnt lgkmcnt(0)
	v_mov_b32_e32 v10, v15
	v_mov_b32_e32 v11, v16
	v_pk_add_f32 v[72:73], v[70:71], v[10:11]
	v_mov_b32_e32 v15, v17
	ds_read_b128 v[10:13], v203 offset:64
	v_pk_add_f32 v[70:71], v[156:157], v[14:15]
	v_pk_mul_f32 v[14:15], v[72:73], v[72:73]
	v_mov_b32_e32 v31, v50
	v_pk_fma_f32 v[14:15], v[70:71], v[70:71], v[14:15]
	s_lshl_b32 s42, s62, 7
	v_pk_add_f32 v[32:33], v[14:15], v[14:15] op_sel:[0,1] op_sel_hi:[1,0]
	ds_read_b128 v[14:17], v203 offset:96
	s_waitcnt lgkmcnt(1)
	v_pk_add_f32 v[66:67], v[66:67], v[10:11]
	v_pk_add_f32 v[64:65], v[68:69], v[12:13]
	v_mul_f32_e32 v10, v67, v67
	v_pk_fma_f32 v[156:157], v[66:67], v[66:67], v[10:11] op_sel_hi:[1,1,0]
	v_mul_f32_e32 v10, v65, v65
	v_pk_fma_f32 v[68:69], v[64:65], v[64:65], v[10:11] op_sel_hi:[1,1,0]
	s_waitcnt lgkmcnt(0)
	v_add_f32_e32 v134, v58, v14
	v_add_f32_e32 v147, v59, v15
	v_add_f32_e32 v149, v60, v16
	v_add_f32_e32 v151, v61, v17
	ds_read_b128 v[10:13], v203 offset:128
	ds_read_b128 v[14:17], v203 offset:160
	v_mov_b32_e32 v157, v50
	v_mul_f32_e32 v204, v134, v134
	v_mul_f32_e32 v206, v147, v147
	v_mul_f32_e32 v208, v149, v149
	s_waitcnt lgkmcnt(0)
	v_mov_b32_e32 v33, v14
	v_mov_b32_e32 v69, v14
	v_mul_f32_e32 v210, v151, v151
	v_pk_add_f32 v[58:59], v[54:55], v[10:11]
	v_pk_add_f32 v[46:47], v[30:31], v[32:33]
	v_pk_add_f32 v[10:11], v[156:157], v[68:69]
	v_mov_b32_e32 v207, v15
	v_mov_b32_e32 v209, v15
	v_pk_add_f32 v[56:57], v[56:57], v[12:13]
	v_add_f32_e32 v61, v52, v16
	v_add_f32_e32 v60, v53, v17
	v_pk_add_f32 v[52:53], v[204:205], v[206:207]
	v_pk_add_f32 v[12:13], v[210:211], v[208:209]
	v_pk_add_f32 v[14:15], v[46:47], v[10:11]
	v_pk_mul_f32 v[10:11], v[46:47], v[10:11]
	v_mul_f32_e32 v54, v61, v61
	v_mov_b32_e32 v15, v11
	v_pk_add_f32 v[10:11], v[52:53], v[12:13]
	v_pk_mul_f32 v[12:13], v[52:53], v[12:13]
	v_mul_f32_e32 v55, v60, v60
	v_mov_b32_e32 v11, v13
	v_pk_add_f32 v[14:15], v[14:15], v[10:11]
	v_mul_f32_e32 v10, v59, v59
	v_pk_fma_f32 v[16:17], v[58:59], v[58:59], v[10:11] op_sel_hi:[1,1,0]
	v_mul_f32_e32 v10, v57, v57
	v_pk_fma_f32 v[30:31], v[56:57], v[56:57], v[10:11] op_sel_hi:[1,1,0]
	v_mov_b32_e32 v17, v55
	v_mov_b32_e32 v31, v54
	ds_read_b128 v[10:13], v203 offset:192
	v_pk_add_f32 v[16:17], v[16:17], v[30:31]
	v_mov_b32_e32 v207, v27
	v_pk_add_f32 v[14:15], v[14:15], v[16:17]
	v_mov_b32_e32 v155, v135
	v_pk_add_f32 v[30:31], v[14:15], v[14:15] op_sel:[0,1] op_sel_hi:[1,0]
	ds_read_b128 v[14:17], v203 offset:224
	s_waitcnt lgkmcnt(1)
	v_mov_b32_e32 v32, v11
	v_mov_b32_e32 v33, v12
	v_pk_add_f32 v[54:55], v[78:79], v[32:33]
	v_mov_b32_e32 v11, v13
	v_pk_add_f32 v[50:51], v[80:81], v[10:11]
	v_pk_mul_f32 v[10:11], v[54:55], v[54:55]
	s_waitcnt lgkmcnt(0)
	v_pk_add_f32 v[32:33], v[42:43], v[14:15]
	v_pk_fma_f32 v[10:11], v[50:51], v[50:51], v[10:11]
	v_pk_add_f32 v[42:43], v[44:45], v[16:17]
	v_pk_add_f32 v[68:69], v[10:11], v[10:11] op_sel:[0,1] op_sel_hi:[1,0]
	v_mul_f32_e32 v10, v33, v33
	v_pk_fma_f32 v[156:157], v[32:33], v[32:33], v[10:11] op_sel_hi:[1,1,0]
	ds_read_b128 v[10:13], v203 offset:256
	ds_read_b128 v[78:81], v203 offset:288
	v_mul_f32_e32 v14, v43, v43
	v_pk_fma_f32 v[204:205], v[42:43], v[42:43], v[14:15] op_sel_hi:[1,1,0]
	v_mov_b32_e32 v31, v26
	s_waitcnt lgkmcnt(1)
	v_add_f32_e32 v46, v38, v10
	v_add_f32_e32 v45, v39, v11
	v_add_f32_e32 v44, v40, v12
	v_add_f32_e32 v40, v41, v13
	ds_read_b128 v[10:13], v203 offset:320
	s_waitcnt lgkmcnt(1)
	v_pk_add_f32 v[16:17], v[34:35], v[78:79]
	v_pk_add_f32 v[14:15], v[36:37], v[80:81]
	ds_read_b128 v[78:81], v203 offset:352
	v_mov_b32_e32 v157, v26
	s_waitcnt lgkmcnt(1)
	v_mov_b32_e32 v69, v10
	v_mov_b32_e32 v205, v10
	v_mul_f32_e32 v206, v46, v46
	v_mul_f32_e32 v208, v45, v45
	v_mul_f32_e32 v210, v44, v44
	v_mul_f32_e32 v212, v40, v40
	v_add_f32_e32 v39, v28, v12
	v_add_f32_e32 v38, v29, v13
	v_pk_add_f32 v[28:29], v[30:31], v[68:69]
	v_pk_add_f32 v[12:13], v[156:157], v[204:205]
	v_mov_b32_e32 v209, v11
	v_mov_b32_e32 v211, v11
	v_pk_add_f32 v[30:31], v[206:207], v[208:209]
	v_pk_add_f32 v[10:11], v[212:213], v[210:211]
	v_pk_add_f32 v[26:27], v[28:29], v[12:13]
	v_pk_mul_f32 v[12:13], v[28:29], v[12:13]
	v_mul_f32_e32 v34, v39, v39
	v_mov_b32_e32 v27, v13
	v_pk_add_f32 v[12:13], v[30:31], v[10:11]
	v_pk_mul_f32 v[10:11], v[30:31], v[10:11]
	v_mul_f32_e32 v35, v38, v38
	v_mov_b32_e32 v13, v11
	v_pk_add_f32 v[10:11], v[26:27], v[12:13]
	v_mul_f32_e32 v12, v17, v17
	v_mul_f32_e32 v26, v15, v15
	v_pk_fma_f32 v[12:13], v[16:17], v[16:17], v[12:13] op_sel_hi:[1,1,0]
	v_pk_fma_f32 v[26:27], v[14:15], v[14:15], v[26:27] op_sel_hi:[1,1,0]
	v_mov_b32_e32 v13, v35
	v_mov_b32_e32 v27, v34
	v_pk_add_f32 v[12:13], v[12:13], v[26:27]
	ds_read_b128 v[208:211], v203 offset:416
	v_pk_add_f32 v[26:27], v[10:11], v[12:13]
	v_add_u32_e32 v10, s63, v172
	v_ashrrev_i32_e32 v11, 31, v10
	v_lshlrev_b64 v[10:11], 10, v[10:11]
	v_lshl_add_u64 v[10:11], s[40:41], 0, v[10:11]
	v_lshl_add_u64 v[10:11], v[10:11], 0, s[60:61]
	v_lshl_add_u64 v[12:13], s[42:43], 2, v[144:145]
	v_lshl_add_u64 v[10:11], v[10:11], 0, v[154:155]
	global_load_dwordx4 v[204:207], v[12:13], off
	global_load_dwordx2 v[68:69], v[10:11], off
	v_pk_add_f32 v[156:157], v[26:27], v[26:27] op_sel:[0,1] op_sel_hi:[1,0]
	s_waitcnt lgkmcnt(1)
	v_mov_b32_e32 v26, v79
	v_mov_b32_e32 v79, v81
	v_mov_b32_e32 v27, v80
	v_pk_add_f32 v[34:35], v[62:63], v[78:79]
	ds_read_b128 v[78:81], v203 offset:384
	v_pk_add_f32 v[36:37], v[48:49], v[26:27]
	s_waitcnt lgkmcnt(1)
	v_add_f32_e32 v28, v18, v208
	v_pk_mul_f32 v[26:27], v[36:37], v[36:37]
	v_add_f32_e32 v30, v19, v209
	v_pk_fma_f32 v[26:27], v[34:35], v[34:35], v[26:27]
	v_add_f32_e32 v153, v20, v210
	v_pk_add_f32 v[48:49], v[26:27], v[26:27] op_sel:[0,1] op_sel_hi:[1,0]
	s_waitcnt lgkmcnt(0)
	v_pk_add_f32 v[26:27], v[22:23], v[78:79]
	v_add_f32_e32 v155, v21, v211
	v_mul_f32_e32 v22, v27, v27
	v_pk_fma_f32 v[62:63], v[26:27], v[26:27], v[22:23] op_sel_hi:[1,1,0]
	v_pk_add_f32 v[22:23], v[24:25], v[80:81]
	ds_read_b128 v[18:21], v203 offset:448
	ds_read_b128 v[78:81], v203 offset:480
	v_mul_f32_e32 v24, v23, v23
	v_pk_fma_f32 v[24:25], v[22:23], v[22:23], v[24:25] op_sel_hi:[1,1,0]
	v_mov_b32_e32 v157, v2
	v_mov_b32_e32 v63, v2
	s_waitcnt lgkmcnt(0)
	v_mov_b32_e32 v49, v78
	v_mov_b32_e32 v25, v78
	v_mul_f32_e32 v208, v28, v28
	v_mul_f32_e32 v210, v30, v30
	v_mul_f32_e32 v212, v153, v153
	v_mul_f32_e32 v214, v155, v155
	v_pk_add_f32 v[8:9], v[8:9], v[20:21]
	v_add_f32_e32 v21, v4, v80
	v_add_f32_e32 v20, v5, v81
	v_pk_add_f32 v[4:5], v[156:157], v[48:49]
	v_pk_add_f32 v[24:25], v[62:63], v[24:25]
	v_mov_b32_e32 v209, v3
	v_mov_b32_e32 v211, v79
	v_mov_b32_e32 v215, v3
	v_mov_b32_e32 v213, v79
	v_pk_add_f32 v[18:19], v[6:7], v[18:19]
	v_pk_add_f32 v[6:7], v[208:209], v[210:211]
	v_pk_add_f32 v[2:3], v[214:215], v[212:213]
	v_pk_add_f32 v[48:49], v[4:5], v[24:25]
	v_pk_mul_f32 v[24:25], v[4:5], v[24:25]
	v_mul_f32_e32 v4, v19, v19
	v_mov_b32_e32 v49, v25
	v_pk_add_f32 v[24:25], v[6:7], v[2:3]
	v_pk_mul_f32 v[2:3], v[6:7], v[2:3]
	v_mul_f32_e32 v41, v21, v21
	v_mov_b32_e32 v25, v3
	v_pk_add_f32 v[2:3], v[48:49], v[24:25]
	v_pk_fma_f32 v[24:25], v[18:19], v[18:19], v[4:5] op_sel_hi:[1,1,0]
	v_mul_f32_e32 v4, v9, v9
	v_mul_f32_e32 v52, v20, v20
	v_pk_fma_f32 v[48:49], v[8:9], v[8:9], v[4:5] op_sel_hi:[1,1,0]
	v_mov_b32_e32 v25, v52
	v_mov_b32_e32 v49, v41
	v_pk_add_f32 v[24:25], v[24:25], v[48:49]
	s_waitcnt vmcnt(0)
	v_lshlrev_b32_e32 v4, 16, v68
	v_pk_add_f32 v[2:3], v[2:3], v[24:25]
	v_and_b32_e32 v6, 0xffff0000, v68
	v_add_f32_e32 v2, v2, v3
	ds_bpermute_b32 v3, v176, v2
	s_waitcnt lgkmcnt(0)
	v_add_f32_e32 v2, v2, v3
	v_fmamk_f32 v2, v2, 0x3c000000, v200
	v_mul_f32_e32 v3, 0x4b800000, v2
	v_cmp_gt_f32_e32 vcc, s47, v2
	s_nop 1
	v_cndmask_b32_e32 v2, v2, v3, vcc
	v_rsq_f32_e32 v2, v2
	s_nop 0
	v_mul_f32_e32 v3, 0x45800000, v2
	v_cndmask_b32_e32 v2, v2, v3, vcc
	v_mul_f32_e32 v3, v74, v2
	v_mul_f32_e32 v3, v204, v3
	v_mul_f32_e32 v3, v3, v4
	v_mul_f32_e32 v4, v76, v2
	v_mul_f32_e32 v4, v205, v4
	v_mul_f32_e32 v4, v4, v6
	v_cvt_pk_bf16_f32 v24, v3, v4
	v_mul_f32_e32 v3, v77, v2
	v_mul_f32_e32 v3, v206, v3
	v_lshlrev_b32_e32 v4, 16, v69
	v_mul_f32_e32 v3, v3, v4
	v_mul_f32_e32 v4, v75, v2
	v_mul_f32_e32 v4, v207, v4
	v_and_b32_e32 v6, 0xffff0000, v69
	v_mul_f32_e32 v4, v4, v6
	v_cvt_pk_bf16_f32 v25, v3, v4
	global_load_dwordx4 v[74:77], v[12:13], off offset:32
	global_load_dwordx2 v[250:251], v[10:11], off offset:16
	global_store_dwordx2 v[10:11], v[24:25], off
	v_mul_f32_e32 v3, v70, v2
	s_waitcnt vmcnt(2)
	v_mul_f32_e32 v3, v74, v3
	s_waitcnt vmcnt(1)
	v_lshlrev_b32_e32 v4, 16, v250
	v_mul_f32_e32 v3, v3, v4
	v_mul_f32_e32 v4, v72, v2
	v_mul_f32_e32 v4, v75, v4
	v_and_b32_e32 v6, 0xffff0000, v250
	v_mul_f32_e32 v4, v4, v6
	v_cvt_pk_bf16_f32 v24, v3, v4
	v_mul_f32_e32 v3, v73, v2
	v_mul_f32_e32 v3, v76, v3
	v_lshlrev_b32_e32 v4, 16, v251
	v_mul_f32_e32 v3, v3, v4
	v_mul_f32_e32 v4, v71, v2
	v_mul_f32_e32 v4, v77, v4
	v_and_b32_e32 v6, 0xffff0000, v251
	v_mul_f32_e32 v4, v4, v6
	v_cvt_pk_bf16_f32 v25, v3, v4
	global_load_dwordx4 v[68:71], v[12:13], off offset:64
	global_load_dwordx2 v[250:251], v[10:11], off offset:32
	global_store_dwordx2 v[10:11], v[24:25], off offset:16
	v_mul_f32_e32 v3, v66, v2
	s_waitcnt vmcnt(2)
	v_mul_f32_e32 v3, v68, v3
	s_waitcnt vmcnt(1)
	v_lshlrev_b32_e32 v4, 16, v250
	v_mul_f32_e32 v3, v3, v4
	v_mul_f32_e32 v4, v67, v2
	v_mul_f32_e32 v4, v69, v4
	v_and_b32_e32 v6, 0xffff0000, v250
	v_mul_f32_e32 v4, v4, v6
	v_cvt_pk_bf16_f32 v24, v3, v4
	v_mul_f32_e32 v3, v64, v2
	v_mul_f32_e32 v3, v70, v3
	v_lshlrev_b32_e32 v4, 16, v251
	v_mul_f32_e32 v3, v3, v4
	v_mul_f32_e32 v4, v65, v2
	v_mul_f32_e32 v4, v71, v4
	v_and_b32_e32 v6, 0xffff0000, v251
	v_mul_f32_e32 v4, v4, v6
	v_cvt_pk_bf16_f32 v25, v3, v4
	global_load_dwordx2 v[48:49], v[10:11], off offset:48
	global_load_dwordx4 v[62:65], v[12:13], off offset:96
	global_store_dwordx2 v[10:11], v[24:25], off offset:32
	v_mul_f32_e32 v3, v134, v2
	v_mul_f32_e32 v24, v151, v2
	v_mul_f32_e32 v4, v147, v2
	v_mul_f32_e32 v6, v149, v2
	s_waitcnt vmcnt(2)
	v_lshlrev_b32_e32 v25, 16, v48
	v_and_b32_e32 v41, 0xffff0000, v48
	v_lshlrev_b32_e32 v48, 16, v49
	v_and_b32_e32 v49, 0xffff0000, v49
	s_waitcnt vmcnt(1)
	v_mul_f32_e32 v3, v3, v62
	v_mul_f32_e32 v24, v24, v65
	v_mul_f32_e32 v4, v4, v63
	v_mul_f32_e32 v6, v6, v64
	v_mul_f32_e32 v3, v3, v25
	v_mul_f32_e32 v25, v24, v49
	v_mul_f32_e32 v4, v4, v41
	v_mul_f32_e32 v6, v6, v48
	v_cvt_pk_bf16_f32 v24, v3, v4
	v_cvt_pk_bf16_f32 v25, v6, v25
	global_load_dwordx2 v[48:49], v[10:11], off offset:64
	global_load_dwordx4 v[62:65], v[12:13], off offset:128
	global_store_dwordx2 v[10:11], v[24:25], off offset:48
	v_mul_f32_e32 v3, v58, v2
	v_mul_f32_e32 v24, v57, v2
	v_mul_f32_e32 v4, v59, v2
	v_mul_f32_e32 v6, v56, v2
	s_waitcnt vmcnt(2)
	v_lshlrev_b32_e32 v25, 16, v48
	v_and_b32_e32 v41, 0xffff0000, v48
	v_lshlrev_b32_e32 v48, 16, v49
	v_and_b32_e32 v49, 0xffff0000, v49
	s_waitcnt vmcnt(1)
	v_mul_f32_e32 v3, v3, v62
	v_mul_f32_e32 v24, v24, v65
	v_mul_f32_e32 v4, v4, v63
	v_mul_f32_e32 v6, v6, v64
	v_mul_f32_e32 v3, v3, v25
	v_mul_f32_e32 v25, v24, v49
	v_mul_f32_e32 v4, v4, v41
	v_mul_f32_e32 v6, v6, v48
	v_cvt_pk_bf16_f32 v24, v3, v4
	v_cvt_pk_bf16_f32 v25, v6, v25
	global_load_dwordx2 v[48:49], v[10:11], off offset:80
	global_load_dwordx4 v[56:59], v[12:13], off offset:160
	global_store_dwordx2 v[10:11], v[24:25], off offset:64
	v_mul_f32_e32 v3, v47, v2
	v_mul_f32_e32 v24, v60, v2
	v_mul_f32_e32 v4, v53, v2
	v_mul_f32_e32 v6, v61, v2
	s_waitcnt vmcnt(2)
	v_lshlrev_b32_e32 v25, 16, v48
	v_and_b32_e32 v41, 0xffff0000, v48
	v_and_b32_e32 v48, 0xffff0000, v49
	s_waitcnt vmcnt(1)
	v_mul_f32_e32 v3, v3, v56
	v_mul_f32_e32 v24, v24, v59
	v_lshlrev_b32_e32 v47, 16, v49
	v_mul_f32_e32 v4, v4, v57
	v_mul_f32_e32 v6, v6, v58
	v_mul_f32_e32 v3, v3, v25
	v_mul_f32_e32 v25, v24, v48
	v_mul_f32_e32 v4, v4, v41
	v_mul_f32_e32 v6, v6, v47
	v_cvt_pk_bf16_f32 v24, v3, v4
	v_cvt_pk_bf16_f32 v25, v6, v25
	global_load_dwordx2 v[48:49], v[10:11], off offset:96
	global_load_dwordx4 v[56:59], v[12:13], off offset:192
	global_store_dwordx2 v[10:11], v[24:25], off offset:80
	v_mul_f32_e32 v3, v50, v2
	v_mul_f32_e32 v24, v51, v2
	v_mul_f32_e32 v4, v54, v2
	v_mul_f32_e32 v6, v55, v2
	s_waitcnt vmcnt(2)
	v_lshlrev_b32_e32 v25, 16, v48
	v_and_b32_e32 v41, 0xffff0000, v48
	v_and_b32_e32 v48, 0xffff0000, v49
	s_waitcnt vmcnt(1)
	v_mul_f32_e32 v3, v3, v56
	v_mul_f32_e32 v24, v24, v59
	v_lshlrev_b32_e32 v47, 16, v49
	v_mul_f32_e32 v4, v4, v57
	v_mul_f32_e32 v6, v6, v58
	v_mul_f32_e32 v3, v3, v25
	v_mul_f32_e32 v25, v24, v48
	v_mul_f32_e32 v4, v4, v41
	v_mul_f32_e32 v6, v6, v47
	v_cvt_pk_bf16_f32 v24, v3, v4
	v_cvt_pk_bf16_f32 v25, v6, v25
	global_load_dwordx2 v[52:53], v[10:11], off offset:112
	global_load_dwordx4 v[48:51], v[12:13], off offset:224
	global_store_dwordx2 v[10:11], v[24:25], off offset:96
	v_mul_f32_e32 v3, v32, v2
	v_mul_f32_e32 v24, v43, v2
	v_mul_f32_e32 v4, v33, v2
	v_mul_f32_e32 v6, v42, v2
	s_waitcnt vmcnt(2)
	v_lshlrev_b32_e32 v25, 16, v52
	v_and_b32_e32 v41, 0xffff0000, v53
	s_waitcnt vmcnt(1)
	v_mul_f32_e32 v3, v3, v48
	v_mul_f32_e32 v24, v24, v51
	v_and_b32_e32 v32, 0xffff0000, v52
	v_lshlrev_b32_e32 v33, 16, v53
	v_mul_f32_e32 v4, v4, v49
	v_mul_f32_e32 v6, v6, v50
	v_mul_f32_e32 v3, v3, v25
	v_mul_f32_e32 v25, v24, v41
	v_mul_f32_e32 v4, v4, v32
	v_mul_f32_e32 v6, v6, v33
	v_cvt_pk_bf16_f32 v24, v3, v4
	v_cvt_pk_bf16_f32 v25, v6, v25
	global_load_dwordx2 v[32:33], v[10:11], off offset:128
	global_load_dwordx4 v[48:51], v[12:13], off offset:256
	global_store_dwordx2 v[10:11], v[24:25], off offset:112
	v_mul_f32_e32 v3, v46, v2
	v_mul_f32_e32 v24, v40, v2
	v_mul_f32_e32 v4, v45, v2
	v_mul_f32_e32 v6, v44, v2
	s_waitcnt vmcnt(2)
	v_lshlrev_b32_e32 v25, 16, v32
	v_lshlrev_b32_e32 v40, 16, v33
	v_and_b32_e32 v33, 0xffff0000, v33
	s_waitcnt vmcnt(1)
	v_mul_f32_e32 v3, v3, v48
	v_mul_f32_e32 v24, v24, v51
	v_and_b32_e32 v32, 0xffff0000, v32
	v_mul_f32_e32 v4, v4, v49
	v_mul_f32_e32 v6, v6, v50
	v_mul_f32_e32 v3, v3, v25
	v_mul_f32_e32 v25, v24, v33
	v_mul_f32_e32 v4, v4, v32
	v_mul_f32_e32 v6, v6, v40
	v_cvt_pk_bf16_f32 v24, v3, v4
	v_cvt_pk_bf16_f32 v25, v6, v25
	global_load_dwordx2 v[32:33], v[10:11], off offset:144
	global_load_dwordx4 v[40:43], v[12:13], off offset:288
	global_store_dwordx2 v[10:11], v[24:25], off offset:128
	v_mul_f32_e32 v3, v16, v2
	v_mul_f32_e32 v6, v14, v2
	v_mul_f32_e32 v14, v15, v2
	v_mul_f32_e32 v4, v17, v2
	s_waitcnt vmcnt(2)
	v_lshlrev_b32_e32 v15, 16, v32
	v_and_b32_e32 v24, 0xffff0000, v33
	s_waitcnt vmcnt(1)
	v_mul_f32_e32 v3, v3, v40
	v_mul_f32_e32 v14, v14, v43
	v_and_b32_e32 v16, 0xffff0000, v32
	v_lshlrev_b32_e32 v17, 16, v33
	v_mul_f32_e32 v4, v4, v41
	v_mul_f32_e32 v6, v6, v42
	v_mul_f32_e32 v3, v3, v15
	v_mul_f32_e32 v15, v14, v24
	v_mul_f32_e32 v4, v4, v16
	v_mul_f32_e32 v6, v6, v17
	v_cvt_pk_bf16_f32 v14, v3, v4
	v_cvt_pk_bf16_f32 v15, v6, v15
	global_load_dwordx2 v[24:25], v[10:11], off offset:160
	v_mul_f32_e32 v3, v29, v2
	global_load_dwordx4 v[246:249], v[12:13], off offset:320
	global_store_dwordx2 v[10:11], v[14:15], off offset:144
	v_mul_f32_e32 v29, v38, v2
	v_mul_f32_e32 v4, v31, v2
	v_mul_f32_e32 v6, v39, v2
	s_waitcnt vmcnt(2)
	v_lshlrev_b32_e32 v32, 16, v25
	v_and_b32_e32 v25, 0xffff0000, v25
	s_waitcnt vmcnt(1)
	v_mul_f32_e32 v3, v3, v246
	v_mul_f32_e32 v14, v29, v249
	v_lshlrev_b32_e32 v31, 16, v24
	v_and_b32_e32 v24, 0xffff0000, v24
	v_mul_f32_e32 v4, v4, v247
	v_mul_f32_e32 v6, v6, v248
	v_mul_f32_e32 v15, v14, v25
	v_mul_f32_e32 v3, v3, v31
	v_mul_f32_e32 v4, v4, v24
	v_mul_f32_e32 v6, v6, v32
	v_cvt_pk_bf16_f32 v14, v3, v4
	v_cvt_pk_bf16_f32 v15, v6, v15
	global_load_dwordx2 v[24:25], v[10:11], off offset:176
	v_mul_f32_e32 v3, v34, v2
	global_load_dwordx4 v[242:245], v[12:13], off offset:352
	global_store_dwordx2 v[10:11], v[14:15], off offset:160
	v_mul_f32_e32 v29, v35, v2
	v_mul_f32_e32 v4, v36, v2
	v_mul_f32_e32 v6, v37, v2
	s_waitcnt vmcnt(2)
	v_lshlrev_b32_e32 v32, 16, v25
	v_and_b32_e32 v25, 0xffff0000, v25
	s_waitcnt vmcnt(1)
	v_mul_f32_e32 v3, v3, v242
	v_mul_f32_e32 v14, v29, v245
	v_lshlrev_b32_e32 v31, 16, v24
	v_and_b32_e32 v24, 0xffff0000, v24
	v_mul_f32_e32 v4, v4, v243
	v_mul_f32_e32 v6, v6, v244
	v_mul_f32_e32 v15, v14, v25
	v_mul_f32_e32 v3, v3, v31
	v_mul_f32_e32 v4, v4, v24
	v_mul_f32_e32 v6, v6, v32
	v_cvt_pk_bf16_f32 v14, v3, v4
	v_cvt_pk_bf16_f32 v15, v6, v15
	global_load_dwordx2 v[24:25], v[10:11], off offset:192
	v_mul_f32_e32 v3, v26, v2
	global_load_dwordx4 v[246:249], v[12:13], off offset:384
	global_store_dwordx2 v[10:11], v[14:15], off offset:176
	v_mul_f32_e32 v6, v22, v2
	v_mul_f32_e32 v22, v23, v2
	v_mul_f32_e32 v4, v27, v2
	s_waitcnt vmcnt(2)
	v_lshlrev_b32_e32 v26, 16, v25
	v_and_b32_e32 v25, 0xffff0000, v25
	s_waitcnt vmcnt(1)
	v_mul_f32_e32 v3, v3, v246
	v_mul_f32_e32 v14, v22, v249
	v_lshlrev_b32_e32 v23, 16, v24
	v_and_b32_e32 v24, 0xffff0000, v24
	v_mul_f32_e32 v4, v4, v247
	v_mul_f32_e32 v6, v6, v248
	v_mul_f32_e32 v15, v14, v25
	v_mul_f32_e32 v3, v3, v23
	v_mul_f32_e32 v4, v4, v24
	v_mul_f32_e32 v6, v6, v26
	v_cvt_pk_bf16_f32 v14, v3, v4
	v_cvt_pk_bf16_f32 v15, v6, v15
	global_load_dwordx2 v[22:23], v[10:11], off offset:208
	v_mul_f32_e32 v3, v28, v2
	global_load_dwordx4 v[242:245], v[12:13], off offset:416
	global_store_dwordx2 v[10:11], v[14:15], off offset:192
	v_mul_f32_e32 v24, v155, v2
	v_mul_f32_e32 v4, v30, v2
	v_mul_f32_e32 v6, v153, v2
	s_waitcnt vmcnt(2)
	v_lshlrev_b32_e32 v26, 16, v23
	v_and_b32_e32 v23, 0xffff0000, v23
	s_waitcnt vmcnt(1)
	v_mul_f32_e32 v3, v3, v242
	v_mul_f32_e32 v14, v24, v245
	v_lshlrev_b32_e32 v25, 16, v22
	v_and_b32_e32 v22, 0xffff0000, v22
	v_mul_f32_e32 v4, v4, v243
	v_mul_f32_e32 v6, v6, v244
	v_mul_f32_e32 v15, v14, v23
	v_mul_f32_e32 v3, v3, v25
	v_mul_f32_e32 v4, v4, v22
	v_mul_f32_e32 v6, v6, v26
	v_cvt_pk_bf16_f32 v14, v3, v4
	v_cvt_pk_bf16_f32 v15, v6, v15
	global_load_dwordx2 v[22:23], v[10:11], off offset:224
	v_mul_f32_e32 v3, v18, v2
	global_load_dwordx4 v[246:249], v[12:13], off offset:448
	global_store_dwordx2 v[10:11], v[14:15], off offset:208
	v_mul_f32_e32 v6, v8, v2
	v_mul_f32_e32 v8, v9, v2
	v_mul_f32_e32 v4, v19, v2
	s_waitcnt vmcnt(2)
	v_lshlrev_b32_e32 v9, 16, v22
	v_and_b32_e32 v18, 0xffff0000, v22
	v_and_b32_e32 v22, 0xffff0000, v23
	s_waitcnt vmcnt(1)
	v_mul_f32_e32 v3, v3, v246
	v_mul_f32_e32 v8, v8, v249
	v_lshlrev_b32_e32 v19, 16, v23
	v_mul_f32_e32 v4, v4, v247
	v_mul_f32_e32 v6, v6, v248
	v_mul_f32_e32 v3, v3, v9
	v_mul_f32_e32 v9, v8, v22
	v_mul_f32_e32 v4, v4, v18
	v_mul_f32_e32 v6, v6, v19
	v_cvt_pk_bf16_f32 v8, v3, v4
	v_cvt_pk_bf16_f32 v9, v6, v9
	global_load_dwordx2 v[16:17], v[10:11], off offset:240
	v_mul_f32_e32 v3, v5, v2
	global_load_dwordx4 v[12:15], v[12:13], off offset:480
	global_store_dwordx2 v[10:11], v[8:9], off offset:224
	v_mul_f32_e32 v4, v7, v2
	v_mul_f32_e32 v5, v21, v2
	v_mul_f32_e32 v2, v20, v2
	s_waitcnt vmcnt(2)
	v_lshlrev_b32_e32 v6, 16, v16
	v_and_b32_e32 v7, 0xffff0000, v16
	s_waitcnt vmcnt(1)
	v_mul_f32_e32 v3, v3, v12
	v_lshlrev_b32_e32 v8, 16, v17
	v_and_b32_e32 v9, 0xffff0000, v17
	v_mul_f32_e32 v4, v4, v13
	v_mul_f32_e32 v5, v5, v14
	v_mul_f32_e32 v2, v2, v15
	v_mul_f32_e32 v3, v3, v6
	v_mul_f32_e32 v4, v4, v7
	v_mul_f32_e32 v5, v5, v8
	v_mul_f32_e32 v6, v2, v9
	v_cvt_pk_bf16_f32 v2, v3, v4
	v_cvt_pk_bf16_f32 v3, v5, v6
	global_store_dwordx2 v[10:11], v[2:3], off offset:240
	s_branch .LBB0_977

.LBB0_1207:
	s_or_b64 exec, exec, s[20:21]
	s_waitcnt lgkmcnt(0)
	s_barrier
	s_and_saveexec_b64 s[20:21], s[16:17]
	s_cbranch_execz .LBB0_1133
	ds_read_b128 v[10:13], v203
	ds_read_b128 v[14:17], v203 offset:32
	v_mov_b32_e32 v205, v51
	v_mov_b32_e32 v211, v51
	v_mov_b32_e32 v213, v27
	s_waitcnt lgkmcnt(1)
	v_mov_b32_e32 v30, v11
	v_mov_b32_e32 v31, v12
	v_mov_b32_e32 v11, v13
	v_pk_add_f32 v[76:77], v[72:73], v[30:31]
	v_pk_add_f32 v[74:75], v[74:75], v[10:11]
	v_pk_mul_f32 v[10:11], v[76:77], v[76:77]
	s_lshl_b32 s22, s68, 8
	v_pk_fma_f32 v[10:11], v[74:75], v[74:75], v[10:11]
	s_mov_b32 s23, s47
	v_pk_add_f32 v[30:31], v[10:11], v[10:11] op_sel:[0,1] op_sel_hi:[1,0]
	s_waitcnt lgkmcnt(0)
	v_mov_b32_e32 v10, v15
	v_mov_b32_e32 v11, v16
	v_pk_add_f32 v[72:73], v[70:71], v[10:11]
	v_mov_b32_e32 v15, v17
	ds_read_b128 v[10:13], v203 offset:64
	v_pk_add_f32 v[70:71], v[156:157], v[14:15]
	v_pk_mul_f32 v[14:15], v[72:73], v[72:73]
	v_mov_b32_e32 v31, v50
	v_pk_fma_f32 v[14:15], v[70:71], v[70:71], v[14:15]
	s_lshl_b32 s46, s68, 7
	v_pk_add_f32 v[32:33], v[14:15], v[14:15] op_sel:[0,1] op_sel_hi:[1,0]
	ds_read_b128 v[14:17], v203 offset:96
	s_waitcnt lgkmcnt(1)
	v_pk_add_f32 v[66:67], v[66:67], v[10:11]
	v_pk_add_f32 v[64:65], v[68:69], v[12:13]
	v_mul_f32_e32 v10, v67, v67
	v_pk_fma_f32 v[156:157], v[66:67], v[66:67], v[10:11] op_sel_hi:[1,1,0]
	v_mul_f32_e32 v10, v65, v65
	v_pk_fma_f32 v[68:69], v[64:65], v[64:65], v[10:11] op_sel_hi:[1,1,0]
	s_waitcnt lgkmcnt(0)
	v_add_f32_e32 v134, v58, v14
	v_add_f32_e32 v147, v59, v15
	v_add_f32_e32 v149, v60, v16
	v_add_f32_e32 v151, v61, v17
	ds_read_b128 v[10:13], v203 offset:128
	ds_read_b128 v[14:17], v203 offset:160
	v_mov_b32_e32 v157, v50
	v_mul_f32_e32 v204, v134, v134
	v_mul_f32_e32 v206, v147, v147
	v_mul_f32_e32 v208, v149, v149
	s_waitcnt lgkmcnt(0)
	v_mov_b32_e32 v33, v14
	v_mov_b32_e32 v69, v14
	v_mul_f32_e32 v210, v151, v151
	v_pk_add_f32 v[58:59], v[54:55], v[10:11]
	v_pk_add_f32 v[46:47], v[30:31], v[32:33]
	v_pk_add_f32 v[10:11], v[156:157], v[68:69]
	v_mov_b32_e32 v207, v15
	v_mov_b32_e32 v209, v15
	v_pk_add_f32 v[56:57], v[56:57], v[12:13]
	v_add_f32_e32 v61, v52, v16
	v_add_f32_e32 v60, v53, v17
	v_pk_add_f32 v[52:53], v[204:205], v[206:207]
	v_pk_add_f32 v[12:13], v[210:211], v[208:209]
	v_pk_add_f32 v[14:15], v[46:47], v[10:11]
	v_pk_mul_f32 v[10:11], v[46:47], v[10:11]
	v_mul_f32_e32 v54, v61, v61
	v_mov_b32_e32 v15, v11
	v_pk_add_f32 v[10:11], v[52:53], v[12:13]
	v_pk_mul_f32 v[12:13], v[52:53], v[12:13]
	v_mul_f32_e32 v55, v60, v60
	v_mov_b32_e32 v11, v13
	v_pk_add_f32 v[14:15], v[14:15], v[10:11]
	v_mul_f32_e32 v10, v59, v59
	v_pk_fma_f32 v[16:17], v[58:59], v[58:59], v[10:11] op_sel_hi:[1,1,0]
	v_mul_f32_e32 v10, v57, v57
	v_pk_fma_f32 v[30:31], v[56:57], v[56:57], v[10:11] op_sel_hi:[1,1,0]
	v_mov_b32_e32 v17, v55
	v_mov_b32_e32 v31, v54
	ds_read_b128 v[10:13], v203 offset:192
	v_pk_add_f32 v[16:17], v[16:17], v[30:31]
	v_mov_b32_e32 v207, v27
	v_pk_add_f32 v[14:15], v[14:15], v[16:17]
	v_mov_b32_e32 v155, v135
	v_pk_add_f32 v[30:31], v[14:15], v[14:15] op_sel:[0,1] op_sel_hi:[1,0]
	ds_read_b128 v[14:17], v203 offset:224
	s_waitcnt lgkmcnt(1)
	v_mov_b32_e32 v32, v11
	v_mov_b32_e32 v33, v12
	v_pk_add_f32 v[54:55], v[78:79], v[32:33]
	v_mov_b32_e32 v11, v13
	v_pk_add_f32 v[50:51], v[80:81], v[10:11]
	v_pk_mul_f32 v[10:11], v[54:55], v[54:55]
	s_waitcnt lgkmcnt(0)
	v_pk_add_f32 v[32:33], v[42:43], v[14:15]
	v_pk_fma_f32 v[10:11], v[50:51], v[50:51], v[10:11]
	v_pk_add_f32 v[42:43], v[44:45], v[16:17]
	v_pk_add_f32 v[68:69], v[10:11], v[10:11] op_sel:[0,1] op_sel_hi:[1,0]
	v_mul_f32_e32 v10, v33, v33
	v_pk_fma_f32 v[156:157], v[32:33], v[32:33], v[10:11] op_sel_hi:[1,1,0]
	ds_read_b128 v[10:13], v203 offset:256
	ds_read_b128 v[78:81], v203 offset:288
	v_mul_f32_e32 v14, v43, v43
	v_pk_fma_f32 v[204:205], v[42:43], v[42:43], v[14:15] op_sel_hi:[1,1,0]
	v_mov_b32_e32 v31, v26
	s_waitcnt lgkmcnt(1)
	v_add_f32_e32 v46, v38, v10
	v_add_f32_e32 v45, v39, v11
	v_add_f32_e32 v44, v40, v12
	v_add_f32_e32 v40, v41, v13
	ds_read_b128 v[10:13], v203 offset:320
	s_waitcnt lgkmcnt(1)
	v_pk_add_f32 v[16:17], v[34:35], v[78:79]
	v_pk_add_f32 v[14:15], v[36:37], v[80:81]
	ds_read_b128 v[78:81], v203 offset:352
	v_mov_b32_e32 v157, v26
	s_waitcnt lgkmcnt(1)
	v_mov_b32_e32 v69, v10
	v_mov_b32_e32 v205, v10
	v_mul_f32_e32 v206, v46, v46
	v_mul_f32_e32 v208, v45, v45
	v_mul_f32_e32 v210, v44, v44
	v_mul_f32_e32 v212, v40, v40
	v_add_f32_e32 v39, v28, v12
	v_add_f32_e32 v38, v29, v13
	v_pk_add_f32 v[28:29], v[30:31], v[68:69]
	v_pk_add_f32 v[12:13], v[156:157], v[204:205]
	v_mov_b32_e32 v209, v11
	v_mov_b32_e32 v211, v11
	v_pk_add_f32 v[30:31], v[206:207], v[208:209]
	v_pk_add_f32 v[10:11], v[212:213], v[210:211]
	v_pk_add_f32 v[26:27], v[28:29], v[12:13]
	v_pk_mul_f32 v[12:13], v[28:29], v[12:13]
	v_mul_f32_e32 v34, v39, v39
	v_mov_b32_e32 v27, v13
	v_pk_add_f32 v[12:13], v[30:31], v[10:11]
	v_pk_mul_f32 v[10:11], v[30:31], v[10:11]
	v_mul_f32_e32 v35, v38, v38
	v_mov_b32_e32 v13, v11
	v_pk_add_f32 v[10:11], v[26:27], v[12:13]
	v_mul_f32_e32 v12, v17, v17
	v_mul_f32_e32 v26, v15, v15
	v_pk_fma_f32 v[12:13], v[16:17], v[16:17], v[12:13] op_sel_hi:[1,1,0]
	v_pk_fma_f32 v[26:27], v[14:15], v[14:15], v[26:27] op_sel_hi:[1,1,0]
	v_mov_b32_e32 v13, v35
	v_mov_b32_e32 v27, v34
	v_pk_add_f32 v[12:13], v[12:13], v[26:27]
	ds_read_b128 v[208:211], v203 offset:416
	v_pk_add_f32 v[26:27], v[10:11], v[12:13]
	v_add_u32_e32 v10, s39, v171
	v_ashrrev_i32_e32 v11, 31, v10
	v_lshlrev_b64 v[10:11], 10, v[10:11]
	v_lshl_add_u64 v[10:11], s[44:45], 0, v[10:11]
	v_lshl_add_u64 v[10:11], v[10:11], 0, s[22:23]
	v_lshl_add_u64 v[12:13], s[46:47], 2, v[144:145]
	v_lshl_add_u64 v[10:11], v[10:11], 0, v[154:155]
	global_load_dwordx4 v[204:207], v[12:13], off
	global_load_dwordx2 v[68:69], v[10:11], off
	v_pk_add_f32 v[156:157], v[26:27], v[26:27] op_sel:[0,1] op_sel_hi:[1,0]
	s_waitcnt lgkmcnt(1)
	v_mov_b32_e32 v26, v79
	v_mov_b32_e32 v79, v81
	v_mov_b32_e32 v27, v80
	v_pk_add_f32 v[34:35], v[62:63], v[78:79]
	ds_read_b128 v[78:81], v203 offset:384
	v_pk_add_f32 v[36:37], v[48:49], v[26:27]
	s_waitcnt lgkmcnt(1)
	v_add_f32_e32 v28, v18, v208
	v_pk_mul_f32 v[26:27], v[36:37], v[36:37]
	v_add_f32_e32 v30, v19, v209
	v_pk_fma_f32 v[26:27], v[34:35], v[34:35], v[26:27]
	v_add_f32_e32 v153, v20, v210
	v_pk_add_f32 v[48:49], v[26:27], v[26:27] op_sel:[0,1] op_sel_hi:[1,0]
	s_waitcnt lgkmcnt(0)
	v_pk_add_f32 v[26:27], v[22:23], v[78:79]
	v_add_f32_e32 v155, v21, v211
	v_mul_f32_e32 v22, v27, v27
	v_pk_fma_f32 v[62:63], v[26:27], v[26:27], v[22:23] op_sel_hi:[1,1,0]
	v_pk_add_f32 v[22:23], v[24:25], v[80:81]
	ds_read_b128 v[18:21], v203 offset:448
	ds_read_b128 v[78:81], v203 offset:480
	v_mul_f32_e32 v24, v23, v23
	v_pk_fma_f32 v[24:25], v[22:23], v[22:23], v[24:25] op_sel_hi:[1,1,0]
	v_mov_b32_e32 v157, v2
	v_mov_b32_e32 v63, v2
	s_waitcnt lgkmcnt(0)
	v_mov_b32_e32 v49, v78
	v_mov_b32_e32 v25, v78
	v_mul_f32_e32 v208, v28, v28
	v_mul_f32_e32 v210, v30, v30
	v_mul_f32_e32 v212, v153, v153
	v_mul_f32_e32 v214, v155, v155
	v_pk_add_f32 v[8:9], v[8:9], v[20:21]
	v_add_f32_e32 v21, v4, v80
	v_add_f32_e32 v20, v5, v81
	v_pk_add_f32 v[4:5], v[156:157], v[48:49]
	v_pk_add_f32 v[24:25], v[62:63], v[24:25]
	v_mov_b32_e32 v209, v3
	v_mov_b32_e32 v211, v79
	v_mov_b32_e32 v215, v3
	v_mov_b32_e32 v213, v79
	v_pk_add_f32 v[18:19], v[6:7], v[18:19]
	v_pk_add_f32 v[6:7], v[208:209], v[210:211]
	v_pk_add_f32 v[2:3], v[214:215], v[212:213]
	v_pk_add_f32 v[48:49], v[4:5], v[24:25]
	v_pk_mul_f32 v[24:25], v[4:5], v[24:25]
	v_mul_f32_e32 v4, v19, v19
	v_mov_b32_e32 v49, v25
	v_pk_add_f32 v[24:25], v[6:7], v[2:3]
	v_pk_mul_f32 v[2:3], v[6:7], v[2:3]
	v_mul_f32_e32 v41, v21, v21
	v_mov_b32_e32 v25, v3
	v_pk_add_f32 v[2:3], v[48:49], v[24:25]
	v_pk_fma_f32 v[24:25], v[18:19], v[18:19], v[4:5] op_sel_hi:[1,1,0]
	v_mul_f32_e32 v4, v9, v9
	v_mul_f32_e32 v52, v20, v20
	v_pk_fma_f32 v[48:49], v[8:9], v[8:9], v[4:5] op_sel_hi:[1,1,0]
	v_mov_b32_e32 v25, v52
	v_mov_b32_e32 v49, v41
	v_pk_add_f32 v[24:25], v[24:25], v[48:49]
	s_waitcnt vmcnt(0)
	v_lshlrev_b32_e32 v4, 16, v68
	v_pk_add_f32 v[2:3], v[2:3], v[24:25]
	v_and_b32_e32 v6, 0xffff0000, v68
	v_add_f32_e32 v2, v2, v3
	ds_bpermute_b32 v3, v175, v2
	s_waitcnt lgkmcnt(0)
	v_add_f32_e32 v2, v2, v3
	v_fmamk_f32 v2, v2, 0x3c000000, v200
	v_mul_f32_e32 v3, 0x4b800000, v2
	v_cmp_gt_f32_e32 vcc, s38, v2
	s_nop 1
	v_cndmask_b32_e32 v2, v2, v3, vcc
	v_rsq_f32_e32 v2, v2
	s_nop 0
	v_mul_f32_e32 v3, 0x45800000, v2
	v_cndmask_b32_e32 v2, v2, v3, vcc
	v_mul_f32_e32 v3, v74, v2
	v_mul_f32_e32 v3, v204, v3
	v_mul_f32_e32 v3, v3, v4
	v_mul_f32_e32 v4, v76, v2
	v_mul_f32_e32 v4, v205, v4
	v_mul_f32_e32 v4, v4, v6
	v_cvt_pk_bf16_f32 v24, v3, v4
	v_mul_f32_e32 v3, v77, v2
	v_mul_f32_e32 v3, v206, v3
	v_lshlrev_b32_e32 v4, 16, v69
	v_mul_f32_e32 v3, v3, v4
	v_mul_f32_e32 v4, v75, v2
	v_mul_f32_e32 v4, v207, v4
	v_and_b32_e32 v6, 0xffff0000, v69
	v_mul_f32_e32 v4, v4, v6
	v_cvt_pk_bf16_f32 v25, v3, v4
	global_load_dwordx4 v[74:77], v[12:13], off offset:32
	global_load_dwordx2 v[250:251], v[10:11], off offset:16
	global_store_dwordx2 v[10:11], v[24:25], off
	v_mul_f32_e32 v3, v70, v2
	s_waitcnt vmcnt(2)
	v_mul_f32_e32 v3, v74, v3
	s_waitcnt vmcnt(1)
	v_lshlrev_b32_e32 v4, 16, v250
	v_mul_f32_e32 v3, v3, v4
	v_mul_f32_e32 v4, v72, v2
	v_mul_f32_e32 v4, v75, v4
	v_and_b32_e32 v6, 0xffff0000, v250
	v_mul_f32_e32 v4, v4, v6
	v_cvt_pk_bf16_f32 v24, v3, v4
	v_mul_f32_e32 v3, v73, v2
	v_mul_f32_e32 v3, v76, v3
	v_lshlrev_b32_e32 v4, 16, v251
	v_mul_f32_e32 v3, v3, v4
	v_mul_f32_e32 v4, v71, v2
	v_mul_f32_e32 v4, v77, v4
	v_and_b32_e32 v6, 0xffff0000, v251
	v_mul_f32_e32 v4, v4, v6
	v_cvt_pk_bf16_f32 v25, v3, v4
	global_load_dwordx4 v[68:71], v[12:13], off offset:64
	global_load_dwordx2 v[250:251], v[10:11], off offset:32
	global_store_dwordx2 v[10:11], v[24:25], off offset:16
	v_mul_f32_e32 v3, v66, v2
	s_waitcnt vmcnt(2)
	v_mul_f32_e32 v3, v68, v3
	s_waitcnt vmcnt(1)
	v_lshlrev_b32_e32 v4, 16, v250
	v_mul_f32_e32 v3, v3, v4
	v_mul_f32_e32 v4, v67, v2
	v_mul_f32_e32 v4, v69, v4
	v_and_b32_e32 v6, 0xffff0000, v250
	v_mul_f32_e32 v4, v4, v6
	v_cvt_pk_bf16_f32 v24, v3, v4
	v_mul_f32_e32 v3, v64, v2
	v_mul_f32_e32 v3, v70, v3
	v_lshlrev_b32_e32 v4, 16, v251
	v_mul_f32_e32 v3, v3, v4
	v_mul_f32_e32 v4, v65, v2
	v_mul_f32_e32 v4, v71, v4
	v_and_b32_e32 v6, 0xffff0000, v251
	v_mul_f32_e32 v4, v4, v6
	v_cvt_pk_bf16_f32 v25, v3, v4
	global_load_dwordx2 v[48:49], v[10:11], off offset:48
	global_load_dwordx4 v[62:65], v[12:13], off offset:96
	global_store_dwordx2 v[10:11], v[24:25], off offset:32
	v_mul_f32_e32 v3, v134, v2
	v_mul_f32_e32 v24, v151, v2
	v_mul_f32_e32 v4, v147, v2
	v_mul_f32_e32 v6, v149, v2
	s_waitcnt vmcnt(2)
	v_lshlrev_b32_e32 v25, 16, v48
	v_and_b32_e32 v41, 0xffff0000, v48
	v_lshlrev_b32_e32 v48, 16, v49
	v_and_b32_e32 v49, 0xffff0000, v49
	s_waitcnt vmcnt(1)
	v_mul_f32_e32 v3, v3, v62
	v_mul_f32_e32 v24, v24, v65
	v_mul_f32_e32 v4, v4, v63
	v_mul_f32_e32 v6, v6, v64
	v_mul_f32_e32 v3, v3, v25
	v_mul_f32_e32 v25, v24, v49
	v_mul_f32_e32 v4, v4, v41
	v_mul_f32_e32 v6, v6, v48
	v_cvt_pk_bf16_f32 v24, v3, v4
	v_cvt_pk_bf16_f32 v25, v6, v25
	global_load_dwordx2 v[48:49], v[10:11], off offset:64
	global_load_dwordx4 v[62:65], v[12:13], off offset:128
	global_store_dwordx2 v[10:11], v[24:25], off offset:48
	v_mul_f32_e32 v3, v58, v2
	v_mul_f32_e32 v24, v57, v2
	v_mul_f32_e32 v4, v59, v2
	v_mul_f32_e32 v6, v56, v2
	s_waitcnt vmcnt(2)
	v_lshlrev_b32_e32 v25, 16, v48
	v_and_b32_e32 v41, 0xffff0000, v48
	v_lshlrev_b32_e32 v48, 16, v49
	v_and_b32_e32 v49, 0xffff0000, v49
	s_waitcnt vmcnt(1)
	v_mul_f32_e32 v3, v3, v62
	v_mul_f32_e32 v24, v24, v65
	v_mul_f32_e32 v4, v4, v63
	v_mul_f32_e32 v6, v6, v64
	v_mul_f32_e32 v3, v3, v25
	v_mul_f32_e32 v25, v24, v49
	v_mul_f32_e32 v4, v4, v41
	v_mul_f32_e32 v6, v6, v48
	v_cvt_pk_bf16_f32 v24, v3, v4
	v_cvt_pk_bf16_f32 v25, v6, v25
	global_load_dwordx2 v[48:49], v[10:11], off offset:80
	global_load_dwordx4 v[56:59], v[12:13], off offset:160
	global_store_dwordx2 v[10:11], v[24:25], off offset:64
	v_mul_f32_e32 v3, v47, v2
	v_mul_f32_e32 v24, v60, v2
	v_mul_f32_e32 v4, v53, v2
	v_mul_f32_e32 v6, v61, v2
	s_waitcnt vmcnt(2)
	v_lshlrev_b32_e32 v25, 16, v48
	v_and_b32_e32 v41, 0xffff0000, v48
	v_and_b32_e32 v48, 0xffff0000, v49
	s_waitcnt vmcnt(1)
	v_mul_f32_e32 v3, v3, v56
	v_mul_f32_e32 v24, v24, v59
	v_lshlrev_b32_e32 v47, 16, v49
	v_mul_f32_e32 v4, v4, v57
	v_mul_f32_e32 v6, v6, v58
	v_mul_f32_e32 v3, v3, v25
	v_mul_f32_e32 v25, v24, v48
	v_mul_f32_e32 v4, v4, v41
	v_mul_f32_e32 v6, v6, v47
	v_cvt_pk_bf16_f32 v24, v3, v4
	v_cvt_pk_bf16_f32 v25, v6, v25
	global_load_dwordx2 v[48:49], v[10:11], off offset:96
	global_load_dwordx4 v[56:59], v[12:13], off offset:192
	global_store_dwordx2 v[10:11], v[24:25], off offset:80
	v_mul_f32_e32 v3, v50, v2
	v_mul_f32_e32 v24, v51, v2
	v_mul_f32_e32 v4, v54, v2
	v_mul_f32_e32 v6, v55, v2
	s_waitcnt vmcnt(2)
	v_lshlrev_b32_e32 v25, 16, v48
	v_and_b32_e32 v41, 0xffff0000, v48
	v_and_b32_e32 v48, 0xffff0000, v49
	s_waitcnt vmcnt(1)
	v_mul_f32_e32 v3, v3, v56
	v_mul_f32_e32 v24, v24, v59
	v_lshlrev_b32_e32 v47, 16, v49
	v_mul_f32_e32 v4, v4, v57
	v_mul_f32_e32 v6, v6, v58
	v_mul_f32_e32 v3, v3, v25
	v_mul_f32_e32 v25, v24, v48
	v_mul_f32_e32 v4, v4, v41
	v_mul_f32_e32 v6, v6, v47
	v_cvt_pk_bf16_f32 v24, v3, v4
	v_cvt_pk_bf16_f32 v25, v6, v25
	global_load_dwordx2 v[52:53], v[10:11], off offset:112
	global_load_dwordx4 v[48:51], v[12:13], off offset:224
	global_store_dwordx2 v[10:11], v[24:25], off offset:96
	v_mul_f32_e32 v3, v32, v2
	v_mul_f32_e32 v24, v43, v2
	v_mul_f32_e32 v4, v33, v2
	v_mul_f32_e32 v6, v42, v2
	s_waitcnt vmcnt(2)
	v_lshlrev_b32_e32 v25, 16, v52
	v_and_b32_e32 v41, 0xffff0000, v53
	s_waitcnt vmcnt(1)
	v_mul_f32_e32 v3, v3, v48
	v_mul_f32_e32 v24, v24, v51
	v_and_b32_e32 v32, 0xffff0000, v52
	v_lshlrev_b32_e32 v33, 16, v53
	v_mul_f32_e32 v4, v4, v49
	v_mul_f32_e32 v6, v6, v50
	v_mul_f32_e32 v3, v3, v25
	v_mul_f32_e32 v25, v24, v41
	v_mul_f32_e32 v4, v4, v32
	v_mul_f32_e32 v6, v6, v33
	v_cvt_pk_bf16_f32 v24, v3, v4
	v_cvt_pk_bf16_f32 v25, v6, v25
	global_load_dwordx2 v[32:33], v[10:11], off offset:128
	global_load_dwordx4 v[48:51], v[12:13], off offset:256
	global_store_dwordx2 v[10:11], v[24:25], off offset:112
	v_mul_f32_e32 v3, v46, v2
	v_mul_f32_e32 v24, v40, v2
	v_mul_f32_e32 v4, v45, v2
	v_mul_f32_e32 v6, v44, v2
	s_waitcnt vmcnt(2)
	v_lshlrev_b32_e32 v25, 16, v32
	v_lshlrev_b32_e32 v40, 16, v33
	v_and_b32_e32 v33, 0xffff0000, v33
	s_waitcnt vmcnt(1)
	v_mul_f32_e32 v3, v3, v48
	v_mul_f32_e32 v24, v24, v51
	v_and_b32_e32 v32, 0xffff0000, v32
	v_mul_f32_e32 v4, v4, v49
	v_mul_f32_e32 v6, v6, v50
	v_mul_f32_e32 v3, v3, v25
	v_mul_f32_e32 v25, v24, v33
	v_mul_f32_e32 v4, v4, v32
	v_mul_f32_e32 v6, v6, v40
	v_cvt_pk_bf16_f32 v24, v3, v4
	v_cvt_pk_bf16_f32 v25, v6, v25
	global_load_dwordx2 v[32:33], v[10:11], off offset:144
	global_load_dwordx4 v[40:43], v[12:13], off offset:288
	global_store_dwordx2 v[10:11], v[24:25], off offset:128
	v_mul_f32_e32 v3, v16, v2
	v_mul_f32_e32 v6, v14, v2
	v_mul_f32_e32 v14, v15, v2
	v_mul_f32_e32 v4, v17, v2
	s_waitcnt vmcnt(2)
	v_lshlrev_b32_e32 v15, 16, v32
	v_and_b32_e32 v24, 0xffff0000, v33
	s_waitcnt vmcnt(1)
	v_mul_f32_e32 v3, v3, v40
	v_mul_f32_e32 v14, v14, v43
	v_and_b32_e32 v16, 0xffff0000, v32
	v_lshlrev_b32_e32 v17, 16, v33
	v_mul_f32_e32 v4, v4, v41
	v_mul_f32_e32 v6, v6, v42
	v_mul_f32_e32 v3, v3, v15
	v_mul_f32_e32 v15, v14, v24
	v_mul_f32_e32 v4, v4, v16
	v_mul_f32_e32 v6, v6, v17
	v_cvt_pk_bf16_f32 v14, v3, v4
	v_cvt_pk_bf16_f32 v15, v6, v15
	global_load_dwordx2 v[24:25], v[10:11], off offset:160
	v_mul_f32_e32 v3, v29, v2
	global_load_dwordx4 v[246:249], v[12:13], off offset:320
	global_store_dwordx2 v[10:11], v[14:15], off offset:144
	v_mul_f32_e32 v29, v38, v2
	v_mul_f32_e32 v4, v31, v2
	v_mul_f32_e32 v6, v39, v2
	s_waitcnt vmcnt(2)
	v_lshlrev_b32_e32 v32, 16, v25
	v_and_b32_e32 v25, 0xffff0000, v25
	s_waitcnt vmcnt(1)
	v_mul_f32_e32 v3, v3, v246
	v_mul_f32_e32 v14, v29, v249
	v_lshlrev_b32_e32 v31, 16, v24
	v_and_b32_e32 v24, 0xffff0000, v24
	v_mul_f32_e32 v4, v4, v247
	v_mul_f32_e32 v6, v6, v248
	v_mul_f32_e32 v15, v14, v25
	v_mul_f32_e32 v3, v3, v31
	v_mul_f32_e32 v4, v4, v24
	v_mul_f32_e32 v6, v6, v32
	v_cvt_pk_bf16_f32 v14, v3, v4
	v_cvt_pk_bf16_f32 v15, v6, v15
	global_load_dwordx2 v[24:25], v[10:11], off offset:176
	v_mul_f32_e32 v3, v34, v2
	global_load_dwordx4 v[242:245], v[12:13], off offset:352
	global_store_dwordx2 v[10:11], v[14:15], off offset:160
	v_mul_f32_e32 v29, v35, v2
	v_mul_f32_e32 v4, v36, v2
	v_mul_f32_e32 v6, v37, v2
	s_waitcnt vmcnt(2)
	v_lshlrev_b32_e32 v32, 16, v25
	v_and_b32_e32 v25, 0xffff0000, v25
	s_waitcnt vmcnt(1)
	v_mul_f32_e32 v3, v3, v242
	v_mul_f32_e32 v14, v29, v245
	v_lshlrev_b32_e32 v31, 16, v24
	v_and_b32_e32 v24, 0xffff0000, v24
	v_mul_f32_e32 v4, v4, v243
	v_mul_f32_e32 v6, v6, v244
	v_mul_f32_e32 v15, v14, v25
	v_mul_f32_e32 v3, v3, v31
	v_mul_f32_e32 v4, v4, v24
	v_mul_f32_e32 v6, v6, v32
	v_cvt_pk_bf16_f32 v14, v3, v4
	v_cvt_pk_bf16_f32 v15, v6, v15
	global_load_dwordx2 v[24:25], v[10:11], off offset:192
	v_mul_f32_e32 v3, v26, v2
	global_load_dwordx4 v[246:249], v[12:13], off offset:384
	global_store_dwordx2 v[10:11], v[14:15], off offset:176
	v_mul_f32_e32 v6, v22, v2
	v_mul_f32_e32 v22, v23, v2
	v_mul_f32_e32 v4, v27, v2
	s_waitcnt vmcnt(2)
	v_lshlrev_b32_e32 v26, 16, v25
	v_and_b32_e32 v25, 0xffff0000, v25
	s_waitcnt vmcnt(1)
	v_mul_f32_e32 v3, v3, v246
	v_mul_f32_e32 v14, v22, v249
	v_lshlrev_b32_e32 v23, 16, v24
	v_and_b32_e32 v24, 0xffff0000, v24
	v_mul_f32_e32 v4, v4, v247
	v_mul_f32_e32 v6, v6, v248
	v_mul_f32_e32 v15, v14, v25
	v_mul_f32_e32 v3, v3, v23
	v_mul_f32_e32 v4, v4, v24
	v_mul_f32_e32 v6, v6, v26
	v_cvt_pk_bf16_f32 v14, v3, v4
	v_cvt_pk_bf16_f32 v15, v6, v15
	global_load_dwordx2 v[22:23], v[10:11], off offset:208
	v_mul_f32_e32 v3, v28, v2
	global_load_dwordx4 v[242:245], v[12:13], off offset:416
	global_store_dwordx2 v[10:11], v[14:15], off offset:192
	v_mul_f32_e32 v24, v155, v2
	v_mul_f32_e32 v4, v30, v2
	v_mul_f32_e32 v6, v153, v2
	s_waitcnt vmcnt(2)
	v_lshlrev_b32_e32 v26, 16, v23
	v_and_b32_e32 v23, 0xffff0000, v23
	s_waitcnt vmcnt(1)
	v_mul_f32_e32 v3, v3, v242
	v_mul_f32_e32 v14, v24, v245
	v_lshlrev_b32_e32 v25, 16, v22
	v_and_b32_e32 v22, 0xffff0000, v22
	v_mul_f32_e32 v4, v4, v243
	v_mul_f32_e32 v6, v6, v244
	v_mul_f32_e32 v15, v14, v23
	v_mul_f32_e32 v3, v3, v25
	v_mul_f32_e32 v4, v4, v22
	v_mul_f32_e32 v6, v6, v26
	v_cvt_pk_bf16_f32 v14, v3, v4
	v_cvt_pk_bf16_f32 v15, v6, v15
	global_load_dwordx2 v[22:23], v[10:11], off offset:224
	v_mul_f32_e32 v3, v18, v2
	global_load_dwordx4 v[246:249], v[12:13], off offset:448
	global_store_dwordx2 v[10:11], v[14:15], off offset:208
	v_mul_f32_e32 v6, v8, v2
	v_mul_f32_e32 v8, v9, v2
	v_mul_f32_e32 v4, v19, v2
	s_waitcnt vmcnt(2)
	v_lshlrev_b32_e32 v9, 16, v22
	v_and_b32_e32 v18, 0xffff0000, v22
	v_and_b32_e32 v22, 0xffff0000, v23
	s_waitcnt vmcnt(1)
	v_mul_f32_e32 v3, v3, v246
	v_mul_f32_e32 v8, v8, v249
	v_lshlrev_b32_e32 v19, 16, v23
	v_mul_f32_e32 v4, v4, v247
	v_mul_f32_e32 v6, v6, v248
	v_mul_f32_e32 v3, v3, v9
	v_mul_f32_e32 v9, v8, v22
	v_mul_f32_e32 v4, v4, v18
	v_mul_f32_e32 v6, v6, v19
	v_cvt_pk_bf16_f32 v8, v3, v4
	v_cvt_pk_bf16_f32 v9, v6, v9
	global_load_dwordx2 v[16:17], v[10:11], off offset:240
	v_mul_f32_e32 v3, v5, v2
	global_load_dwordx4 v[12:15], v[12:13], off offset:480
	global_store_dwordx2 v[10:11], v[8:9], off offset:224
	v_mul_f32_e32 v4, v7, v2
	v_mul_f32_e32 v5, v21, v2
	v_mul_f32_e32 v2, v20, v2
	s_waitcnt vmcnt(2)
	v_lshlrev_b32_e32 v6, 16, v16
	v_and_b32_e32 v7, 0xffff0000, v16
	s_waitcnt vmcnt(1)
	v_mul_f32_e32 v3, v3, v12
	v_lshlrev_b32_e32 v8, 16, v17
	v_and_b32_e32 v9, 0xffff0000, v17
	v_mul_f32_e32 v4, v4, v13
	v_mul_f32_e32 v5, v5, v14
	v_mul_f32_e32 v2, v2, v15
	v_mul_f32_e32 v3, v3, v6
	v_mul_f32_e32 v4, v4, v7
	v_mul_f32_e32 v5, v5, v8
	v_mul_f32_e32 v6, v2, v9
	v_cvt_pk_bf16_f32 v2, v3, v4
	v_cvt_pk_bf16_f32 v3, v5, v6
	global_store_dwordx2 v[10:11], v[2:3], off offset:240
	s_branch .LBB0_1133
